# MLA loop: strength-reduced tile load addressing (32-bit offsets from a scalar base), split max / row-sum dependency chains
# speedup vs baseline: 1.0145x; 1.0007x over previous
; DI int ltid() { int t = threadIdx.x; asm volatile("" : "+v"(t)); return t; }
; #define QUEUE_BEGIN(n) for (;;) { __syncthreads(); if (tid == 0) *s_item = atomicAdd(WSP(int, WS_CTR) + ph + 50 * rep_, 1); __syncthreads(); const int item = *s_item; if (item >= (n)) break;
; __global__ void __launch_bounds__(512, 2) mega(Params p) {
;     ...
;             case OP_ATT_MLA: {
;     ...
;                 const int tid = ltid();
;                 QUEUE_BEGIN(512 + 256)
.LBB0_109:
	s_andn2_b64 vcc, exec, s[6:7]
	s_cbranch_vccnz .LBB0_223
	s_load_dwordx2 s[4:5], s[70:71], 0xe8
	v_readlane_b32 s0, v254, 6
	v_readlane_b32 s1, v254, 7
	s_lshl_b64 s[0:1], s[0:1], 2
	v_mov_b32_e32 v2, v202
	s_waitcnt lgkmcnt(0)
	s_add_u32 s0, s4, s0
	s_addc_u32 s1, s5, s1
	v_writelane_b32 v255, s0, 11
	s_nop 0
	v_lshrrev_b32_e32 v0, 1, v2
	v_writelane_b32 v255, s1, 12
	s_add_u32 s0, s4, 0xcb4a200
	s_addc_u32 s1, s5, 0
	v_writelane_b32 v255, s0, 13
	v_and_b32_e32 v0, 28, v0
	v_cmp_eq_u32_e64 s[12:13], 0, v2
	v_writelane_b32 v255, s1, 14
	s_add_u32 s0, s4, 0x1a349200
	v_writelane_b32 v255, s0, 15
	s_addc_u32 s0, s5, 0
	v_writelane_b32 v255, s0, 16
	s_add_u32 s0, s4, 0xcb49600
	v_writelane_b32 v255, s0, 17
	s_addc_u32 s0, s5, 0
	v_writelane_b32 v255, s0, 18
	s_add_u32 s0, s4, 0xcb49a00
	s_addc_u32 s1, s5, 0
	v_writelane_b32 v255, s0, 19
	v_ashrrev_i32_e32 v196, 6, v2
	v_add_u32_e32 v197, 0xffffc000, v196
	v_writelane_b32 v255, s1, 20
	s_nop 0
	v_readlane_b32 s0, v255, 9
	v_readlane_b32 s1, v255, 10
	s_nop 1
	v_lshl_add_u64 v[136:137], s[0:1], 0, v[0:1]
	v_readlane_b32 s0, v255, 7
	v_lshlrev_b32_e32 v0, 4, v2
	v_readlane_b32 s1, v255, 8
	v_writelane_b32 v255, s12, 21
	v_and_b32_e32 v0, 0x3f0, v0
	v_lshl_add_u64 v[138:139], s[0:1], 0, v[0:1]
	v_writelane_b32 v255, s13, 22
	v_lshl_add_u64 v[2:3], s[4:5], 0, v[0:1]
	s_mov_b64 s[0:1], 0x1ab49200
	v_writelane_b32 v255, s70, 23
	v_lshl_add_u64 v[140:141], v[2:3], 0, s[0:1]
	s_nop 0
	v_writelane_b32 v255, s71, 24
	v_readlane_b32 s99, v255, 1
	s_cmp_eq_u32 s99, 0x100
	s_cselect_b32 s99, 1, 0
	s_branch .LBB0_114

.LBB0_118:
	s_or_b64 exec, exec, s[6:7]
	s_mov_b32 s0, 0x20000
	s_addk_i32 s0, 0x100
	v_mov_b32_e32 v0, s0
	s_waitcnt lgkmcnt(0)
	s_barrier
	ds_read_b32 v0, v0
	v_readlane_b32 s1, v255, 1
	s_cmp_eq_u32 s1, 0x100
	s_cselect_b32 s1, 0x100, 0
	s_movk_i32 s0, 0x31f
	s_sub_i32 s0, s0, s1
	s_mov_b64 s[6:7], -1
	s_waitcnt lgkmcnt(0)
	v_cmp_lt_i32_e32 vcc, s0, v0
	v_readfirstlane_b32 s18, v0
	s_cbranch_vccnz .LBB0_113
	s_add_i32 s18, s18, s1

; #define LAS __attribute__((address_space(3)))
; DI int ltid() { int t = threadIdx.x; asm volatile("" : "+v"(t)); return t; }
; template <int MODE>
; DI void attn_unit(LAS unsigned char* lds, const AttnArgs a) {
;     constexpr int DK = ACfg<MODE>::DK, DV = ACfg<MODE>::DV, KLD = DK + 8, VLD = 72, NKS = DK / 16, NDB = DV / 32;
;     const int tid = ltid(), wid = __builtin_amdgcn_readfirstlane(tid >> 6), lane = tid & 63, r32 = lane & 31, hh = lane >> 5;
;     constexpr bool SWZ = (DV == 64);
;     constexpr int BUFE = 64 * KLD + DV * VLD;
;     LAS bf16_t* Ks = (LAS bf16_t*)lds;
;     LAS bf16_t* Vt = Ks + 64 * KLD;
;     LAS float* biasL = (LAS float*)(Ks + 2 * BUFE);
;     const int q0w = a.q0 + wid * 32, qi = q0w + r32;
;     const size_t qtok = (size_t)a.toff + (size_t)qi * a.tstride;
.LBB0_122:
	s_andn2_b64 vcc, exec, s[6:7]
	s_cbranch_vccnz .LBB0_187
	v_readlane_b32 s100, v255, 13
	v_readlane_b32 s101, v255, 14
	s_and_b32 s1, s18, 7
	s_mul_i32 s0, s1, 0xc0
	v_readlane_b32 s4, v254, 57
	v_readlane_b32 s5, v254, 58
	s_add_u32 s8, s4, s0
	s_addc_u32 s9, s5, 0
	s_lshl_b32 s0, s1, 8
	v_readlane_b32 s4, v254, 55
	v_readlane_b32 s5, v254, 56
	s_add_u32 s6, s4, s0
	s_addc_u32 s7, s5, 0
	s_lshl_b32 s5, s18, 9
	v_mov_b32_e32 v12, v202
	s_lshl_b32 s0, s18, 3
	s_and_b32 s66, s5, 0x1000
	s_and_b32 s0, s0, 0xffffff80
	s_cmpk_lt_i32 s18, 0x40
	s_cselect_b32 s32, 1, 0
	s_cbranch_scc1 .Lq_half
	s_sub_i32 s0, s18, 0x40
	s_lshl_b32 s0, s0, 4
	s_and_b32 s0, s0, 0xffffff00
	s_addk_i32 s0, 0x280

.LBB0_145:
	s_or_b64 exec, exec, s[14:15]
	global_load_dwordx4 v[120:123], v[8:9], off
	v_subrev_u32_e32 v248, s100, v8

; #define LAS __attribute__((address_space(3)))
; template <int MODE>
; DI void attn_unit(LAS unsigned char* lds, const AttnArgs a) {
;     ...
;     for (int it = it0; it < ntile; ++it) {
;         const int kbase = ATT_KBASE(it), cur = (it - it0) & 1;
;         const LAS bf16_t* Kc = Ks + cur * BUFE; const LAS bf16_t* Vc = Vt + cur * BUFE;
.LBB0_151:
	s_or_b64 exec, exec, s[14:15]
	global_load_dwordx4 v[124:127], v[10:11], off
	v_subrev_u32_e32 v249, s100, v10
.LBB0_152:
	s_or_b64 exec, exec, s[8:9]
	v_add_u32_e32 v6, 64, v2
	v_ashrrev_i32_e32 v7, 31, v6
	v_lshl_add_u64 v[6:7], v[6:7], 0, s[66:67]
	v_lshlrev_b64 v[6:7], 11, v[6:7]
	v_lshl_add_u64 v[6:7], s[6:7], 0, v[6:7]
	v_lshl_add_u64 v[6:7], v[4:5], 1, v[6:7]
	global_load_dwordx4 v[128:131], v[6:7], off offset:128
	v_subrev_u32_e32 v250, s100, v6
.LBB0_153:
	s_mov_b64 s[8:9], -1
	s_cmpk_gt_i32 s4, 0xfec1
	v_lshlrev_b32_e32 v198, 2, v48
	s_cbranch_scc0 .LBB0_184
	v_lshlrev_b32_e32 v142, 2, v48
	v_lshl_add_u64 v[144:145], v[4:5], 1, s[6:7]
	v_lshrrev_b32_e32 v4, 1, v12
	v_and_b32_e32 v5, 12, v4
	v_bitop3_b32 v200, v142, v4, 12 bitop3:0x78
	v_or_b32_e32 v4, 32, v13
	v_or_b32_e32 v3, 8, v142
	v_lshrrev_b32_e32 v4, 1, v4
	v_or_b32_e32 v6, 16, v142
	v_or_b32_e32 v7, 24, v142
	v_or_b32_e32 v8, 32, v142
	v_or_b32_e32 v9, 40, v142
	v_or_b32_e32 v10, 48, v142
	v_or_b32_e32 v11, 56, v142
	v_bitop3_b32 v215, v4, v3, 28 bitop3:0x6c
	v_add_u32_e32 v3, v15, v14
	v_bitop3_b32 v214, v4, v142, 28 bitop3:0x6c
	v_bitop3_b32 v216, v4, v6, 28 bitop3:0x6c
	v_bitop3_b32 v217, v4, v7, 28 bitop3:0x6c
	v_bitop3_b32 v218, v4, v8, 28 bitop3:0x6c
	v_bitop3_b32 v219, v4, v9, 28 bitop3:0x6c
	v_bitop3_b32 v220, v4, v10, 28 bitop3:0x6c
	v_bitop3_b32 v221, v4, v11, 28 bitop3:0x6c
	v_mul_lo_u32 v4, v3, 12
	s_movk_i32 s8, 0x90
	v_sub_u32_e32 v4, v12, v4
	v_add_u32_e32 v6, v52, v51
	v_bitop3_b32 v201, v142, v5, 8 bitop3:0x36
	v_bitop3_b32 v205, v142, v5, 16 bitop3:0x36
	v_bitop3_b32 v208, v142, v5, 24 bitop3:0x36
	v_bitop3_b32 v209, v142, v5, 32 bitop3:0x36
	v_bitop3_b32 v210, v142, v5, 40 bitop3:0x36
	v_bitop3_b32 v211, v142, v5, 48 bitop3:0x36
	v_bitop3_b32 v212, v142, v5, 56 bitop3:0x36
	v_mad_u32_u24 v213, v13, s8, v238
	s_movk_i32 s8, 0xd0
	v_lshlrev_b32_e32 v223, 4, v4
	v_mul_lo_u32 v5, v6, 12
	v_cmp_gt_i32_e64 s[14:15], 8, v4
	v_lshlrev_b32_e32 v4, 3, v4
	v_mul_lo_u32 v222, v3, s8
	v_sub_u32_e32 v7, v50, v5
	v_mul_lo_u32 v224, v6, s8
	v_ashrrev_i32_e32 v5, 31, v4
	v_readlane_b32 s8, v255, 13
	v_lshl_add_u64 v[146:147], v[4:5], 1, s[6:7]
	v_mov_b32_e32 v5, v1
	v_readlane_b32 s9, v255, 14
	s_sub_i32 s0, 0xfff, s0
	s_cmp_lg_u32 s32, 0
	s_cselect_b32 s4, 0, 0x80
	s_add_i32 s0, s0, s4
	s_ashr_i32 s4, s0, 31
	v_lshl_add_u64 v[148:149], v[4:5], 1, s[8:9]
	v_lshlrev_b32_e32 v4, 3, v7
	v_ashrrev_i32_e32 v5, 31, v4
	s_lshr_b32 s4, s4, 26
	v_lshl_add_u64 v[150:151], v[4:5], 1, s[6:7]
	v_mov_b32_e32 v5, v1
	s_add_i32 s0, s0, s4
	v_mul_u32_u24_e32 v0, 0xd0, v13
	v_lshl_add_u64 v[152:153], v[4:5], 1, s[8:9]
	v_lshlrev_b32_e32 v4, 1, v49
	s_movk_i32 s6, 0x100
	v_mov_b32_e32 v14, v1
	v_mov_b32_e32 v15, v1
	s_ashr_i32 s0, s0, 6
	v_mul_u32_u24_e32 v199, 0x90, v13
	v_lshlrev_b32_e32 v225, 4, v7
	v_cmp_gt_i32_e64 s[16:17], 8, v7
	v_add3_u32 v226, s6, v0, v4
	v_add_u32_e32 v227, 0x80, v3
	v_add_u32_e32 v228, 0x80, v6
	v_add_u32_e32 v229, 0x80, v2
	v_mov_b32_e32 v0, v1
	v_mov_b32_e32 v2, v1
	v_mov_b32_e32 v3, v1
	v_mov_b32_e32 v4, v1
	v_mov_b32_e32 v6, v1
	v_mov_b32_e32 v7, v1
	v_mov_b32_e32 v8, v1
	v_mov_b32_e32 v9, v1
	v_mov_b32_e32 v10, v1
	v_mov_b32_e32 v11, v1
	v_mov_b32_e32 v12, v1
	v_mov_b32_e32 v13, v1
	v_mov_b64_e32 v[30:31], v[14:15]
	v_mov_b64_e32 v[46:47], v[14:15]
	s_or_b32 s4, s19, 31
	s_cmp_lg_u32 s98, 0
	s_cselect_b32 s4, -1, s4
	s_mov_b32 s5, 0
	s_max_i32 s20, s0, 0
	v_mov_b32_e32 v135, v134
	v_mov_b32_e32 v230, 0
	v_mov_b32_e32 v232, 0xf149f2ca
	v_mov_b64_e32 v[28:29], v[12:13]
	v_mov_b64_e32 v[26:27], v[10:11]
	v_mov_b64_e32 v[24:25], v[8:9]
	v_mov_b64_e32 v[22:23], v[6:7]
	v_mov_b64_e32 v[20:21], v[4:5]
	v_mov_b64_e32 v[18:19], v[2:3]
	v_mov_b64_e32 v[16:17], v[0:1]
	v_mov_b64_e32 v[44:45], v[12:13]
	v_mov_b64_e32 v[42:43], v[10:11]
	v_mov_b64_e32 v[40:41], v[8:9]
	v_mov_b64_e32 v[38:39], v[6:7]
	v_mov_b64_e32 v[36:37], v[4:5]
	v_mov_b64_e32 v[34:35], v[2:3]
	v_mov_b64_e32 v[32:33], v[0:1]
	v_and_b32_e32 v214, 63, v202
	v_and_b32_e32 v215, 3, v214
	v_bfe_u32 v216, v214, 2, 2
	v_bfe_u32 v217, v214, 4, 1
	v_bfe_u32 v218, v214, 5, 1
	v_lshrrev_b32_e32 v219, 1, v215
	v_lshl_or_b32 v219, v217, 1, v219
	v_and_b32_e32 v220, 2, v216
	v_lshl_or_b32 v219, v220, 1, v219
	v_lshlrev_b32_e32 v219, 4, v219
	v_and_b32_e32 v215, 1, v215
	v_lshl_or_b32 v219, v215, 3, v219
	v_lshl_or_b32 v219, v216, 7, v219
	v_lshl_or_b32 v200, v218, 9, v219
	v_xor_b32_e32 v201, 64, v200
	v_mov_b32_e32 v251, 0x138000
	v_mov_b32_e32 v207, 0x20000
	v_cndmask_b32_e64 v204, v251, v207, s[14:15]
	v_cndmask_b32_e64 v206, v251, v207, s[16:17]
	s_mov_b32 s21, 0
	s_and_b32 s8, s21, 1
	s_cmp_gt_i32 s5, s4
	s_cbranch_scc0 .LBB0_156

; #define LAS __attribute__((address_space(3)))
; DI float ex2(float x) { return __builtin_amdgcn_exp2f(x); }
; DI float max3f(float a, float b, float c) { float r; asm("v_max3_f32 %0, %1, %2, %3" : "=v"(r) : "v"(a), "v"(b), "v"(c)); return r; }
; #define MFMA32(a, b, c) __builtin_amdgcn_mfma_f32_32x32x16_bf16((a), (b), (c), 0, 0, 0)
; template <int MODE>
; DI void attn_unit(LAS unsigned char* lds, const AttnArgs a) {
;     ...
; #pragma unroll
;         for (int ks = 0; ks < NKS; ++ks) {
;             const bf16x8 a0 = *(const LAS bf16x8*)(Kc + r32 * KLD + ks * 16 + 8 * hh);
;             const bf16x8 a1 = *(const LAS bf16x8*)(Kc + (32 + r32) * KLD + ks * 16 + 8 * hh);
;             s0 = MFMA32(a0, qf[ks], s0); s1 = MFMA32(a1, qf[ks], s1);
;         }
;         if (MODE == 2) {
;             if (kbase + 63 < q0w) { sb_block<false>(s1, kbase + 32, qi, hh, a.c2, carry); sb_block<false>(s0, kbase, qi, hh, a.c2, carry); }
;             else                  { sb_block<true>(s1, kbase + 32, qi, hh, a.c2, carry);  sb_block<true>(s0, kbase, qi, hh, a.c2, carry); }
;         } else {
;             const bool interior = (MODE == 0) || (MODE == 1 && kbase + 63 <= q0w);
;             float mnew, alpha, ls = 0.f;
;             if (interior) {
; #pragma unroll
;                 for (int i = 0; i < 16; ++i) { s0[i] *= a.c2; s1[i] *= a.c2; }
;                 float mx = max3f(s0[0], s1[0], s0[1]);
;                 mx = max3f(mx, s1[1], s0[2]); mx = max3f(mx, s1[2], s0[3]); mx = max3f(mx, s1[3], s0[4]); mx = max3f(mx, s1[4], s0[5]);
;                 mx = max3f(mx, s1[5], s0[6]); mx = max3f(mx, s1[6], s0[7]); mx = max3f(mx, s1[7], s0[8]); mx = max3f(mx, s1[8], s0[9]);
;                 mx = max3f(mx, s1[9], s0[10]); mx = max3f(mx, s1[10], s0[11]); mx = max3f(mx, s1[11], s0[12]); mx = max3f(mx, s1[12], s0[13]);
;                 mx = max3f(mx, s1[13], s0[14]); mx = max3f(mx, s1[14], s0[15]); mx = fmaxf(mx, s1[15]);
;                 mx = fmaxf(mx, __shfl_xor(mx, 32));
;                 mnew = fmaxf(mrow, mx); alpha = ex2(mrow - mnew);
; #pragma unroll
;                 for (int i = 0; i < 16; ++i) {
;                     const float p0 = ex2(s0[i] - mnew), p1 = ex2(s1[i] - mnew);
;                     s0[i] = p0; s1[i] = p1; ls += p0 + p1;
;                 }
.LBB0_156:
	s_mul_i32 s9, s8, 0x2c00
	v_lshl_add_u32 v0, s9, 1, v226
	ds_read_b128 v[2:5], v0
	ds_read_b128 v[6:9], v0 offset:6656
	ds_read_b128 v[10:13], v0 offset:32
	ds_read_b128 v[64:67], v0 offset:6688
	ds_read_b128 v[68:71], v0 offset:64
	ds_read_b128 v[72:75], v0 offset:6720
	ds_read_b128 v[76:79], v0 offset:96
	ds_read_b128 v[154:157], v0 offset:6752
	ds_read_b128 v[158:161], v0 offset:128
	ds_read_b128 v[162:165], v0 offset:6784
	ds_read_b128 v[166:169], v0 offset:160
	ds_read_b128 v[170:173], v0 offset:6816
	s_add_i32 s22, s5, 63
	s_mov_b64 s[6:7], -1
	s_cmp_gt_i32 s22, s19
	s_waitcnt lgkmcnt(11)
	v_mfma_f32_32x32x16_bf16 v[48:63], v[2:5], v[96:99], 0
	s_waitcnt lgkmcnt(10)
	v_mfma_f32_32x32x16_bf16 v[80:95], v[6:9], v[96:99], 0
	s_waitcnt lgkmcnt(9)
	v_mfma_f32_32x32x16_bf16 v[48:63], v[10:13], v[100:103], v[48:63]
	s_waitcnt lgkmcnt(8)
	v_mfma_f32_32x32x16_bf16 v[80:95], v[64:67], v[100:103], v[80:95]
	s_waitcnt lgkmcnt(7)
	v_mfma_f32_32x32x16_bf16 v[48:63], v[68:71], v[104:107], v[48:63]
	s_waitcnt lgkmcnt(6)
	v_mfma_f32_32x32x16_bf16 v[80:95], v[72:75], v[104:107], v[80:95]
	s_waitcnt lgkmcnt(5)
	v_mfma_f32_32x32x16_bf16 v[48:63], v[76:79], v[108:111], v[48:63]
	s_waitcnt lgkmcnt(4)
	v_mfma_f32_32x32x16_bf16 v[80:95], v[154:157], v[108:111], v[80:95]
	s_waitcnt lgkmcnt(3)
	v_mfma_f32_32x32x16_bf16 v[48:63], v[158:161], v[112:115], v[48:63]
	s_waitcnt lgkmcnt(2)
	v_mfma_f32_32x32x16_bf16 v[80:95], v[162:165], v[112:115], v[80:95]
	s_waitcnt lgkmcnt(1)
	v_mfma_f32_32x32x16_bf16 v[48:63], v[166:169], v[116:119], v[48:63]
	s_waitcnt lgkmcnt(0)
	v_mfma_f32_32x32x16_bf16 v[80:95], v[170:173], v[116:119], v[80:95]
	s_nop 9
	v_mul_f32_e32 v5, 0x3e16c740, v48
	v_mul_f32_e32 v3, 0x3e16c740, v49
	s_cbranch_scc1 .LBB0_182
	v_max3_f32 v0, v48, v49, v50
	v_max3_f32 v14, v80, v81, v82
	v_max3_f32 v0, v0, v51, v52
	v_max3_f32 v14, v14, v83, v84
	v_max3_f32 v0, v0, v53, v54
	v_max3_f32 v14, v14, v85, v86
	v_max3_f32 v0, v0, v55, v56
	v_max3_f32 v14, v14, v87, v88
	v_max3_f32 v0, v0, v57, v58
	v_max3_f32 v14, v14, v89, v90
	v_max3_f32 v0, v0, v59, v60
	v_max3_f32 v14, v14, v91, v92
	v_max3_f32 v0, v0, v61, v62
	v_max3_f32 v14, v14, v93, v94
	v_max3_f32 v0, v0, v63, v14
	v_and_b32_e32 v4, 64, v243
	v_xor_b32_e32 v5, 32, v243
	v_add_u32_e32 v4, 64, v4
	v_cmp_lt_i32_e32 vcc, v5, v4
	v_max_f32_e32 v0, v0, v95
	v_mul_f32_e32 v0, 0x3e16c740, v0
	v_cndmask_b32_e32 v5, v243, v5, vcc
	v_lshlrev_b32_e32 v5, 2, v5
	ds_bpermute_b32 v3, v5, v0
	s_lshl_b32 s7, s9, 1
	s_mov_b32 s6, 0x3e16c740
	v_add_u32_e32 v158, s7, v200
	v_add_u32_e32 v159, s7, v201
	ds_read_b64_tr_b16 v[64:65], v158 offset:13568
	ds_read_b64_tr_b16 v[66:67], v158 offset:14592
	ds_read_b64_tr_b16 v[68:69], v159 offset:13568
	ds_read_b64_tr_b16 v[70:71], v159 offset:14592
	ds_read_b64_tr_b16 v[72:73], v158 offset:15616
	ds_read_b64_tr_b16 v[74:75], v158 offset:16640
	ds_read_b64_tr_b16 v[76:77], v159 offset:15616
	ds_read_b64_tr_b16 v[78:79], v159 offset:16640
	s_waitcnt lgkmcnt(8)
	v_max3_f32 v231, v232, v0, v3
	v_sub_f32_e32 v2, v232, v231
	v_exp_f32_e32 v2, v2
	v_fma_f32 v48, v48, s6, -v231
	v_fma_f32 v49, v49, s6, -v231
	v_fma_f32 v50, v50, s6, -v231
	v_fma_f32 v51, v51, s6, -v231
	v_fma_f32 v52, v52, s6, -v231
	v_fma_f32 v53, v53, s6, -v231
	v_fma_f32 v54, v54, s6, -v231
	v_fma_f32 v55, v55, s6, -v231
	v_cmp_gt_f32_e32 vcc, 1.0, v2
	s_cbranch_vccz .Lmla_f_nors
	v_pk_mul_f32 v[46:47], v[46:47], v[2:3] op_sel_hi:[1,0]
	v_pk_mul_f32 v[44:45], v[44:45], v[2:3] op_sel_hi:[1,0]
	v_pk_mul_f32 v[42:43], v[42:43], v[2:3] op_sel_hi:[1,0]
	v_pk_mul_f32 v[40:41], v[40:41], v[2:3] op_sel_hi:[1,0]
	v_pk_mul_f32 v[38:39], v[38:39], v[2:3] op_sel_hi:[1,0]
	v_pk_mul_f32 v[36:37], v[36:37], v[2:3] op_sel_hi:[1,0]
	v_pk_mul_f32 v[34:35], v[34:35], v[2:3] op_sel_hi:[1,0]
	v_pk_mul_f32 v[32:33], v[32:33], v[2:3] op_sel_hi:[1,0]
	v_pk_mul_f32 v[30:31], v[30:31], v[2:3] op_sel_hi:[1,0]
	v_pk_mul_f32 v[28:29], v[28:29], v[2:3] op_sel_hi:[1,0]
	v_pk_mul_f32 v[26:27], v[26:27], v[2:3] op_sel_hi:[1,0]
	v_pk_mul_f32 v[24:25], v[24:25], v[2:3] op_sel_hi:[1,0]
	v_pk_mul_f32 v[22:23], v[22:23], v[2:3] op_sel_hi:[1,0]
	v_pk_mul_f32 v[20:21], v[20:21], v[2:3] op_sel_hi:[1,0]
	v_pk_mul_f32 v[18:19], v[18:19], v[2:3] op_sel_hi:[1,0]
	v_pk_mul_f32 v[16:17], v[16:17], v[2:3] op_sel_hi:[1,0]
; template <int MODE>
; DI void attn_unit(LAS unsigned char* lds, const AttnArgs a) {
;     ...
; #pragma unroll
;                 for (int i = 0; i < 16; ++i) {
;                     const float p0 = ex2(s0[i] - mnew), p1 = ex2(s1[i] - mnew);
;                     s0[i] = p0; s1[i] = p1; ls += p0 + p1;
;                 }
;             } else {
;                 float mx = -1e30f;
; #pragma unroll
;                 for (int i = 0; i < 16; ++i) {
;                     const int k0 = kbase + crow(i, hh), k1 = k0 + 32;
;                     float x0 = s0[i] * a.c2, x1 = s1[i] * a.c2;
;                     bool v0 = true, v1 = true;
;                     if (MODE == 1) { v0 = k0 <= qi; v1 = k1 <= qi; }
;                     if (MODE == 3) {
;                         const int st0 = qi - k0, st1 = qi - k1;
;                         v0 = (st0 >= 0) && (st0 <= 128) && (k0 >= 0); v1 = (st1 >= 0) && (st1 <= 128) && (k1 >= 0);
;                         x0 += biasL[min(max(st0, 0), 128)]; x1 += biasL[min(max(st1, 0), 128)];
;                     }
;                     x0 = v0 ? x0 : -1e30f; x1 = v1 ? x1 : -1e30f;
;                     s0[i] = x0; s1[i] = x1; mx = fmaxf(mx, fmaxf(x0, x1));
;                 }
;                 mx = fmaxf(mx, __shfl_xor(mx, 32));
;                 mnew = fmaxf(mrow, mx); alpha = ex2(mrow - mnew);
; #pragma unroll
;                 for (int i = 0; i < 16; ++i) {
;                     const float p0 = (s0[i] > -1e29f) ? ex2(s0[i] - mnew) : 0.f, p1 = (s1[i] > -1e29f) ? ex2(s1[i] - mnew) : 0.f;
;                     s0[i] = p0; s1[i] = p1; ls += p0 + p1;
;                 }
;             }
;             mrow = mnew;
;             lrow = lrow * alpha + ls;
;             if (__ballot(alpha < 1.0f) != 0ull) {
; #pragma unroll
;                 for (int d = 0; d < NDB; ++d)
; #pragma unroll
;                     for (int i = 0; i < 16; ++i) o[d][i] *= alpha;
;             }
;         }
;         const bf16x8 pb00 = pack8(s0, 0), pb01 = pack8(s0, 1), pb10 = pack8(s1, 0), pb11 = pack8(s1, 1);
; #pragma unroll
;         for (int d = 0; d < NDB; ++d) {
;             const LAS bf16_t* vp = Vc + (d * 32 + r32) * VLD;
;             const int sw = SWZ ? ((((d * 32 + r32) >> 3) & 7) << 2) : 0;
;     ...
;             o[d] = MFMA32(VFRAG(0), pb00, o[d]);
;             o[d] = MFMA32(VFRAG(16), pb01, o[d]);
;             o[d] = MFMA32(VFRAG(32), pb10, o[d]);
.Lmla_f_nors:
	v_exp_f32_e32 v48, v48
	v_exp_f32_e32 v49, v49
	v_exp_f32_e32 v50, v50
	v_exp_f32_e32 v51, v51
	v_exp_f32_e32 v52, v52
	v_exp_f32_e32 v53, v53
	v_exp_f32_e32 v54, v54
	v_exp_f32_e32 v55, v55
	v_pk_add_f32 v[160:161], v[48:49], v[50:51]
	v_pk_add_f32 v[162:163], v[52:53], v[54:55]
	v_cvt_pk_bf16_f32 v4, v48, v49
	v_cvt_pk_bf16_f32 v5, v50, v51
	v_cvt_pk_bf16_f32 v6, v52, v53
	v_cvt_pk_bf16_f32 v7, v54, v55
	s_nop 1
	s_waitcnt lgkmcnt(4)
	v_mfma_f32_32x32x16_bf16 v[32:47], v[64:67], v[4:7], v[32:47]
	v_mfma_f32_32x32x16_bf16 v[16:31], v[68:71], v[4:7], v[16:31]
	ds_read_b64_tr_b16 v[64:65], v158 offset:17664
	ds_read_b64_tr_b16 v[66:67], v158 offset:18688
	ds_read_b64_tr_b16 v[68:69], v159 offset:17664
	ds_read_b64_tr_b16 v[70:71], v159 offset:18688
	v_fma_f32 v56, v56, s6, -v231
	v_fma_f32 v57, v57, s6, -v231
	v_fma_f32 v58, v58, s6, -v231
	v_fma_f32 v59, v59, s6, -v231
	v_fma_f32 v60, v60, s6, -v231
	v_fma_f32 v61, v61, s6, -v231
	v_fma_f32 v62, v62, s6, -v231
	v_fma_f32 v63, v63, s6, -v231
	v_exp_f32_e32 v56, v56
	v_exp_f32_e32 v57, v57
	v_exp_f32_e32 v58, v58
	v_exp_f32_e32 v59, v59
	v_exp_f32_e32 v60, v60
	v_exp_f32_e32 v61, v61
	v_exp_f32_e32 v62, v62
	v_exp_f32_e32 v63, v63
	v_pk_add_f32 v[160:161], v[160:161], v[56:57]
	v_pk_add_f32 v[162:163], v[162:163], v[58:59]
	v_pk_add_f32 v[160:161], v[160:161], v[60:61]
	v_pk_add_f32 v[162:163], v[162:163], v[62:63]
	v_cvt_pk_bf16_f32 v8, v56, v57
	v_cvt_pk_bf16_f32 v9, v58, v59
	v_cvt_pk_bf16_f32 v10, v60, v61
	v_cvt_pk_bf16_f32 v11, v62, v63
	s_nop 1
	s_waitcnt lgkmcnt(4)
	v_mfma_f32_32x32x16_bf16 v[32:47], v[72:75], v[8:11], v[32:47]
	v_mfma_f32_32x32x16_bf16 v[16:31], v[76:79], v[8:11], v[16:31]
	ds_read_b64_tr_b16 v[72:73], v158 offset:19712
	ds_read_b64_tr_b16 v[74:75], v158 offset:20736
	ds_read_b64_tr_b16 v[76:77], v159 offset:19712
	ds_read_b64_tr_b16 v[78:79], v159 offset:20736
	v_fma_f32 v80, v80, s6, -v231
	v_fma_f32 v81, v81, s6, -v231
	v_fma_f32 v82, v82, s6, -v231
	v_fma_f32 v83, v83, s6, -v231
	v_fma_f32 v84, v84, s6, -v231
	v_fma_f32 v85, v85, s6, -v231
	v_fma_f32 v86, v86, s6, -v231
	v_fma_f32 v87, v87, s6, -v231
	v_exp_f32_e32 v80, v80
	v_exp_f32_e32 v81, v81
	v_exp_f32_e32 v82, v82
	v_exp_f32_e32 v83, v83
	v_exp_f32_e32 v84, v84
	v_exp_f32_e32 v85, v85
	v_exp_f32_e32 v86, v86
	v_exp_f32_e32 v87, v87
	v_pk_add_f32 v[160:161], v[160:161], v[80:81]
	v_pk_add_f32 v[162:163], v[162:163], v[82:83]
	v_pk_add_f32 v[160:161], v[160:161], v[84:85]
	v_pk_add_f32 v[162:163], v[162:163], v[86:87]
	v_cvt_pk_bf16_f32 v12, v80, v81
	v_cvt_pk_bf16_f32 v13, v82, v83
	v_cvt_pk_bf16_f32 v14, v84, v85
	v_cvt_pk_bf16_f32 v15, v86, v87
	s_nop 1
	s_waitcnt lgkmcnt(4)
	v_mfma_f32_32x32x16_bf16 v[32:47], v[64:67], v[12:15], v[32:47]
	v_mfma_f32_32x32x16_bf16 v[16:31], v[68:71], v[12:15], v[16:31]
	v_fma_f32 v88, v88, s6, -v231
	v_fma_f32 v89, v89, s6, -v231
	v_fma_f32 v90, v90, s6, -v231
	v_fma_f32 v91, v91, s6, -v231
	v_fma_f32 v92, v92, s6, -v231
	v_fma_f32 v93, v93, s6, -v231
	v_fma_f32 v94, v94, s6, -v231
	v_fma_f32 v95, v95, s6, -v231
	v_exp_f32_e32 v88, v88
	v_exp_f32_e32 v89, v89
	v_exp_f32_e32 v90, v90
	v_exp_f32_e32 v91, v91
	v_exp_f32_e32 v92, v92
	v_exp_f32_e32 v93, v93
	v_exp_f32_e32 v94, v94
	v_exp_f32_e32 v95, v95
	v_pk_add_f32 v[160:161], v[160:161], v[88:89]
	v_pk_add_f32 v[162:163], v[162:163], v[90:91]
	v_pk_add_f32 v[160:161], v[160:161], v[92:93]
	v_pk_add_f32 v[162:163], v[162:163], v[94:95]
	v_cvt_pk_bf16_f32 v154, v88, v89
	v_cvt_pk_bf16_f32 v155, v90, v91
	v_cvt_pk_bf16_f32 v156, v92, v93
	v_cvt_pk_bf16_f32 v157, v94, v95
	s_nop 1
	s_waitcnt lgkmcnt(0)
	v_mfma_f32_32x32x16_bf16 v[32:47], v[72:75], v[154:157], v[32:47]
	v_mfma_f32_32x32x16_bf16 v[16:31], v[76:79], v[154:157], v[16:31]
	v_pk_add_f32 v[160:161], v[160:161], v[162:163]
	v_add_f32_e32 v160, v160, v161
	v_fmac_f32_e32 v160, v230, v2
	v_mov_b32_e32 v230, v160
	s_branch .Lmla_pvj

; template <int MODE>
; DI void attn_unit(LAS unsigned char* lds, const AttnArgs a) {
;     ...
;         if (it + 2 < ntile) ATT_LOAD(it + 2);
.LBB0_166:
	s_add_i32 s6, s21, 2
	s_cmp_gt_i32 s6, s0
	s_waitcnt lgkmcnt(0)
	s_barrier
	s_cbranch_scc1 .LBB0_180
	s_and_saveexec_b64 s[6:7], s[10:11]
	v_add_u32_e32 v248, v248, v204
	global_load_dwordx4 v[120:123], v248, s[100:101]
	s_or_b64 exec, exec, s[6:7]
	s_and_saveexec_b64 s[6:7], s[12:13]
	s_cbranch_execz .Lmla_l2
	v_add_u32_e32 v249, v249, v206
	global_load_dwordx4 v[124:127], v249, s[100:101]
.Lmla_l2:
	s_or_b64 exec, exec, s[6:7]
	v_add_u32_e32 v250, 0x20000, v250
	global_load_dwordx4 v[128:131], v250, s[100:101] offset:128
